# FoX attention softmax front rewritten with packed f32 (v_pk_fma_f32 for S*c+bias, v_pk_add_f32 for t-m), front emitted before the PV part; waits/hazard pads re-derived
# speedup vs baseline: 1.0145x; 1.0145x over previous
; DEVI unsigned pk_bf16(float lo, float hi) { unsigned r; asm("v_cvt_pk_bf16_f32 %0, %1, %2" : "=v"(r) : "v"(lo), "v"(hi)); return r; }
; DEVI bf16x8 mk8(uint2 a, uint2 b) { union { uint4 u; bf16x8 v; } c; c.u = make_uint4(a.x, a.y, b.x, b.y); return c.v; }
; template <int DK, bool BIAS> ...
;     ...
;       for (int qi = 0; qi < 2; ++qi) {
;         float mx = -3e38f;
;         if (BIAS) {
; #pragma unroll
;           for (int kt = 0; kt < 4; ++kt) { const f32x4 nf = *(const f32x4*)(fkm + buf * 64 + 16 * kt + 4 * fq);
; #pragma unroll
;             for (int r = 0; r < 4; ++r) { const float t = fmaf(S[kt][qi][r], sc2, nf[r]); S[kt][qi][r] = t; mx = fmaxf(mx, t); } }
;         } else {
; #pragma unroll
;           for (int kt = 0; kt < 4; ++kt)
; #pragma unroll
;             for (int r = 0; r < 4; ++r) mx = fmaxf(mx, S[kt][qi][r]);
;           mx *= sc2;
;         }
;         mx = fmaxf(mx, __shfl_xor(mx, 16)); mx = fmaxf(mx, __shfl_xor(mx, 32));
;         const float mold = mrun[qi], mnew = fmaxf(mold, mx);
;         mrun[qi] = mnew;
;         float ps = 0.f;
; #pragma unroll
;         for (int kt = 0; kt < 4; ++kt)
; #pragma unroll
;           for (int r = 0; r < 4; ++r) { const float pv = BIAS ? __builtin_amdgcn_exp2f(S[kt][qi][r] - mnew) : __builtin_amdgcn_exp2f(fmaf(S[kt][qi][r], sc2, -mnew)); S[kt][qi][r] = pv; ps += pv; }
;         {
;           const float alpha = __builtin_amdgcn_exp2f(mold - mnew);
;           lrun[qi] *= alpha;
; #pragma unroll
;           for (int et = 0; et < 4; ++et) O[et][qi] *= alpha;
;         }
;         lrun[qi] += ps;
; #pragma unroll
;         for (int k2 = 0; k2 < 2; ++k2) { uint2 lo, hi; lo.x = pk_bf16(S[2 * k2][qi][0], S[2 * k2][qi][1]); lo.y = pk_bf16(S[2 * k2][qi][2], S[2 * k2][qi][3]);
;           hi.x = pk_bf16(S[2 * k2 + 1][qi][0], S[2 * k2 + 1][qi][1]); hi.y = pk_bf16(S[2 * k2 + 1][qi][2], S[2 * k2 + 1][qi][3]); pf[qi][k2] = mk8(lo, hi); }
;       }
.LBB0_1776:
	s_or_b64 exec, exec, s[18:19]
	ds_read_b128 v[174:177], v168 offset:36864
	ds_read_b128 v[194:197], v168 offset:36928
	ds_read_b128 v[242:245], v168 offset:36992
	ds_read_b128 v[246:249], v168 offset:37056
	s_mov_b32 s100, 0x3e38aa3b
	s_mov_b32 s101, 0x3e38aa3b
	v_cmp_lt_i32_e32 vcc, v186, v184
	s_nop 1
	v_cndmask_b32_e32 v250, v183, v186, vcc
	v_cmp_lt_i32_e32 vcc, v185, v184
	s_nop 1
	v_cndmask_b32_e32 v251, v183, v185, vcc
	v_lshlrev_b32_e32 v250, 2, v250
	v_lshlrev_b32_e32 v251, 2, v251
	s_waitcnt lgkmcnt(3)
	v_pk_fma_f32 v[210:211], v[80:81], s[100:101], v[174:175]
	v_pk_fma_f32 v[212:213], v[82:83], s[100:101], v[176:177]
	v_pk_fma_f32 v[226:227], v[64:65], s[100:101], v[174:175]
	v_pk_fma_f32 v[228:229], v[66:67], s[100:101], v[176:177]
	s_waitcnt lgkmcnt(2)
	v_pk_fma_f32 v[214:215], v[86:87], s[100:101], v[194:195]
	v_pk_fma_f32 v[216:217], v[88:89], s[100:101], v[196:197]
	v_pk_fma_f32 v[230:231], v[68:69], s[100:101], v[194:195]
	v_pk_fma_f32 v[232:233], v[70:71], s[100:101], v[196:197]
	s_waitcnt lgkmcnt(1)
	v_pk_fma_f32 v[218:219], v[90:91], s[100:101], v[242:243]
	v_pk_fma_f32 v[220:221], v[92:93], s[100:101], v[244:245]
	v_pk_fma_f32 v[234:235], v[72:73], s[100:101], v[242:243]
	v_pk_fma_f32 v[236:237], v[74:75], s[100:101], v[244:245]
	s_waitcnt lgkmcnt(0)
	v_pk_fma_f32 v[222:223], v[94:95], s[100:101], v[246:247]
	v_pk_fma_f32 v[224:225], v[96:97], s[100:101], v[248:249]
	v_pk_fma_f32 v[238:239], v[76:77], s[100:101], v[246:247]
	v_pk_fma_f32 v[240:241], v[78:79], s[100:101], v[248:249]
	v_max3_f32 v84, v210, s31, v211
	v_max3_f32 v85, v226, s31, v227
	v_max3_f32 v84, v84, v212, v213
	v_max3_f32 v85, v85, v228, v229
	v_max3_f32 v84, v84, v214, v215
	v_max3_f32 v85, v85, v230, v231
	v_max3_f32 v84, v84, v216, v217
	v_max3_f32 v85, v85, v232, v233
	v_max3_f32 v84, v84, v218, v219
	v_max3_f32 v85, v85, v234, v235
	v_max3_f32 v84, v84, v220, v221
	v_max3_f32 v85, v85, v236, v237
	v_max3_f32 v84, v84, v222, v223
	v_max3_f32 v85, v85, v238, v239
	v_max3_f32 v84, v84, v224, v225
	v_max3_f32 v85, v85, v240, v241
	ds_bpermute_b32 v86, v250, v84
	ds_bpermute_b32 v87, v250, v85
	s_waitcnt lgkmcnt(0)
	v_max_f32_e32 v84, v84, v86
	v_max_f32_e32 v85, v85, v87
	ds_bpermute_b32 v86, v251, v84
	ds_bpermute_b32 v87, v251, v85
	s_waitcnt lgkmcnt(0)
	v_max3_f32 v131, v114, v84, v86
	v_max3_f32 v173, v112, v85, v87
	v_sub_f32_e32 v84, v114, v131
	v_sub_f32_e32 v85, v112, v173
	v_exp_f32_e32 v126, v84
	v_exp_f32_e32 v82, v85
	v_sub_f32_e32 v86, 0, v131
	v_sub_f32_e32 v80, 0, v173
	v_pk_add_f32 v[210:211], v[210:211], v[86:87] op_sel_hi:[1,0]
	v_pk_add_f32 v[212:213], v[212:213], v[86:87] op_sel_hi:[1,0]
	v_pk_add_f32 v[226:227], v[226:227], v[80:81] op_sel_hi:[1,0]
	v_pk_add_f32 v[228:229], v[228:229], v[80:81] op_sel_hi:[1,0]
	v_pk_add_f32 v[214:215], v[214:215], v[86:87] op_sel_hi:[1,0]
	v_pk_add_f32 v[216:217], v[216:217], v[86:87] op_sel_hi:[1,0]
	v_pk_add_f32 v[230:231], v[230:231], v[80:81] op_sel_hi:[1,0]
	v_pk_add_f32 v[232:233], v[232:233], v[80:81] op_sel_hi:[1,0]
	v_pk_add_f32 v[218:219], v[218:219], v[86:87] op_sel_hi:[1,0]
	v_pk_add_f32 v[220:221], v[220:221], v[86:87] op_sel_hi:[1,0]
	v_pk_add_f32 v[234:235], v[234:235], v[80:81] op_sel_hi:[1,0]
	v_pk_add_f32 v[236:237], v[236:237], v[80:81] op_sel_hi:[1,0]
	v_pk_add_f32 v[222:223], v[222:223], v[86:87] op_sel_hi:[1,0]
	v_pk_add_f32 v[224:225], v[224:225], v[86:87] op_sel_hi:[1,0]
	v_pk_add_f32 v[238:239], v[238:239], v[80:81] op_sel_hi:[1,0]
	v_pk_add_f32 v[240:241], v[240:241], v[80:81] op_sel_hi:[1,0]
	v_exp_f32_e32 v155, v210
	v_exp_f32_e32 v154, v226
	v_exp_f32_e32 v157, v211
	v_exp_f32_e32 v156, v227
	v_exp_f32_e32 v151, v212
	v_exp_f32_e32 v150, v228
	v_exp_f32_e32 v153, v213
	v_exp_f32_e32 v152, v229
	v_exp_f32_e32 v117, v214
	v_exp_f32_e32 v116, v230
	v_exp_f32_e32 v119, v215
	v_exp_f32_e32 v118, v231
	v_exp_f32_e32 v123, v216
	v_exp_f32_e32 v122, v232
	v_exp_f32_e32 v121, v217
	v_exp_f32_e32 v120, v233
	v_exp_f32_e32 v125, v218
	v_exp_f32_e32 v124, v234
	v_exp_f32_e32 v89, v219
	v_exp_f32_e32 v88, v235
	v_exp_f32_e32 v95, v220
	v_exp_f32_e32 v94, v236
	v_exp_f32_e32 v115, v221
	v_exp_f32_e32 v114, v237
	v_exp_f32_e32 v93, v222
	v_exp_f32_e32 v92, v238
	v_exp_f32_e32 v113, v223
	v_exp_f32_e32 v112, v239
	v_exp_f32_e32 v91, v224
	v_exp_f32_e32 v90, v240
	v_exp_f32_e32 v97, v225
	v_exp_f32_e32 v96, v241
	v_pk_mul_f32 v[202:203], v[52:53], v[126:127] op_sel_hi:[1,0]
	v_pk_mul_f32 v[52:53], v[56:57], v[126:127] op_sel_hi:[1,0]
	v_pk_mul_f32 v[198:199], v[48:49], v[126:127] op_sel_hi:[1,0]
	v_pk_mul_f32 v[48:49], v[60:61], v[126:127] op_sel_hi:[1,0]
	v_add_u32_e32 v174, 0x4800, v170
	v_add_u32_e32 v175, 0x5000, v170
	v_pk_mul_f32 v[200:201], v[50:51], v[126:127] op_sel_hi:[1,0]
	v_add_u32_e32 v176, 0x5800, v170
	v_pk_mul_f32 v[204:205], v[54:55], v[126:127] op_sel_hi:[1,0]
	v_pk_add_f32 v[64:65], v[154:155], 0 op_sel_hi:[1,0]
	v_pk_add_f32 v[80:81], v[156:157], v[64:65]
	ds_read2_b64 v[64:67], v174 offset1:4
	ds_read2_b64 v[72:75], v175 offset0:32 offset1:36
	v_pk_mul_f32 v[46:47], v[46:47], v[82:83] op_sel_hi:[1,0]
	v_pk_mul_f32 v[44:45], v[44:45], v[82:83] op_sel_hi:[1,0]
	v_pk_mul_f32 v[54:55], v[58:59], v[126:127] op_sel_hi:[1,0]
	v_cvt_pk_bf16_f32 v56, v155, v157
	v_cvt_pk_bf16_f32 v57, v151, v153
	v_cvt_pk_bf16_f32 v58, v117, v119
	v_cvt_pk_bf16_f32 v59, v123, v121
	v_cvt_pk_bf16_f32 v68, v154, v156
	s_waitcnt lgkmcnt(1)
; DEVI unsigned pk_bf16(float lo, float hi) { unsigned r; asm("v_cvt_pk_bf16_f32 %0, %1, %2" : "=v"(r) : "v"(lo), "v"(hi)); return r; }
; DEVI bf16x8 mk8(uint2 a, uint2 b) { union { uint4 u; bf16x8 v; } c; c.u = make_uint4(a.x, a.y, b.x, b.y); return c.v; }
; #define MFMA(a, b, c) __builtin_amdgcn_mfma_f32_16x16x32_bf16((a), (b), (c), 0, 0, 0)
; template <int DK, bool BIAS> ...
;     ...
;         {
;           const float alpha = __builtin_amdgcn_exp2f(mold - mnew);
;           lrun[qi] *= alpha;
; #pragma unroll
;           for (int et = 0; et < 4; ++et) O[et][qi] *= alpha;
;         }
;         lrun[qi] += ps;
; #pragma unroll
;         for (int k2 = 0; k2 < 2; ++k2) { uint2 lo, hi; lo.x = pk_bf16(S[2 * k2][qi][0], S[2 * k2][qi][1]); lo.y = pk_bf16(S[2 * k2][qi][2], S[2 * k2][qi][3]);
;           hi.x = pk_bf16(S[2 * k2 + 1][qi][0], S[2 * k2 + 1][qi][1]); hi.y = pk_bf16(S[2 * k2 + 1][qi][2], S[2 * k2 + 1][qi][3]); pf[qi][k2] = mk8(lo, hi); }
;       }
; #pragma unroll
;       for (int k2 = 0; k2 < 2; ++k2)
; #pragma unroll
;         for (int et = 0; et < 4; ++et) {
;           const uint2 v0 = *(const uint2*)(Vtm + (buf * 64 + 16 * et + fr) * 72 + 32 * k2 + 4 * fq), v1 = *(const uint2*)(Vtm + (buf * 64 + 16 * et + fr) * 72 + 32 * k2 + 16 + 4 * fq);
;           const bf16x8 va = mk8(v0, v1);
; #pragma unroll
;           for (int qi = 0; qi < 2; ++qi) O[et][qi] = MFMA(va, pf[qi][k2], O[et][qi]);
;         }
	v_mfma_f32_16x16x32_bf16 v[76:79], v[64:67], v[56:59], v[198:201]
	v_cvt_pk_bf16_f32 v69, v150, v152
	v_cvt_pk_bf16_f32 v70, v116, v118
	v_cvt_pk_bf16_f32 v71, v122, v120
	v_mul_f32_e64 v42, v42, v82
	v_mul_f32_e64 v43, v43, v82
	v_mfma_f32_16x16x32_bf16 v[44:47], v[64:67], v[68:71], v[44:47]
	ds_read2_b64 v[64:67], v176 offset0:64 offset1:68
	v_pk_mul_f32 v[40:41], v[40:41], v[82:83] op_sel_hi:[1,0]
	v_add_u32_e32 v177, 0x6000, v170
	s_waitcnt lgkmcnt(1)
	v_mfma_f32_16x16x32_bf16 v[84:87], v[72:75], v[56:59], v[202:205]
	v_pk_mul_f32 v[50:51], v[62:63], v[126:127] op_sel_hi:[1,0]
	v_mfma_f32_16x16x32_bf16 v[40:43], v[72:75], v[68:71], v[40:43]
	ds_read2_b64 v[72:75], v177 offset0:96 offset1:100
	v_pk_mul_f32 v[38:39], v[38:39], v[82:83] op_sel_hi:[1,0]
	v_pk_mul_f32 v[36:37], v[36:37], v[82:83] op_sel_hi:[1,0]
	s_waitcnt lgkmcnt(1)
	v_mfma_f32_16x16x32_bf16 v[154:157], v[64:67], v[56:59], v[52:55]
	v_mul_f32_e64 v34, v34, v82
	v_mul_f32_e64 v35, v35, v82
	v_pk_mul_f32 v[32:33], v[32:33], v[82:83] op_sel_hi:[1,0]
	v_cvt_pk_bf16_f32 v60, v125, v89
	v_mfma_f32_16x16x32_bf16 v[36:39], v[64:67], v[68:71], v[36:39]
	ds_read2_b64 v[52:55], v174 offset0:8 offset1:12
	s_waitcnt lgkmcnt(1)
	v_mfma_f32_16x16x32_bf16 v[64:67], v[72:75], v[56:59], v[48:51]
	ds_read2_b64 v[56:59], v175 offset0:40 offset1:44
	v_cvt_pk_bf16_f32 v61, v95, v115
	v_cvt_pk_bf16_f32 v62, v93, v113
	v_cvt_pk_bf16_f32 v63, v91, v97
	s_nop 0
	v_mfma_f32_16x16x32_bf16 v[32:35], v[72:75], v[68:71], v[32:35]
	v_cvt_pk_bf16_f32 v68, v124, v88
	v_cvt_pk_bf16_f32 v69, v94, v114
	s_waitcnt lgkmcnt(1)
	v_mfma_f32_16x16x32_bf16 v[48:51], v[52:55], v[60:63], v[76:79]
	v_cvt_pk_bf16_f32 v70, v92, v112
	v_cvt_pk_bf16_f32 v71, v90, v96
	ds_read2_b64 v[72:75], v176 offset0:72 offset1:76
	s_nop 0
	v_mfma_f32_16x16x32_bf16 v[44:47], v[52:55], v[68:71], v[44:47]
	v_add_f32_e64 v52, v150, v80
	v_add_f32_e64 v53, v151, v81
	v_mov_b32_e32 v83, v126
	v_pk_add_f32 v[76:77], v[152:153], v[52:53]
	s_waitcnt lgkmcnt(1)
	v_mfma_f32_16x16x32_bf16 v[52:55], v[56:59], v[60:63], v[84:87]
	v_add_f32_e64 v76, v116, v76
	v_add_f32_e64 v77, v117, v77
	v_pk_add_f32 v[76:77], v[118:119], v[76:77]
	v_mfma_f32_16x16x32_bf16 v[40:43], v[56:59], v[68:71], v[40:43]
	v_add_f32_e64 v76, v122, v76
	v_add_f32_e64 v77, v123, v77
	v_pk_add_f32 v[56:57], v[120:121], v[76:77]
	ds_read2_b64 v[76:79], v177 offset0:104 offset1:108
	v_pk_add_f32 v[80:81], v[124:125], v[56:57]
	s_waitcnt lgkmcnt(1)
	v_mfma_f32_16x16x32_bf16 v[56:59], v[72:75], v[60:63], v[154:157]
	v_add_f32_e64 v80, v88, v80
	v_add_f32_e64 v81, v89, v81
	v_pk_add_f32 v[80:81], v[94:95], v[80:81]
	v_mfma_f32_16x16x32_bf16 v[36:39], v[72:75], v[68:71], v[36:39]
	v_add_f32_e64 v80, v114, v80
	v_add_f32_e64 v81, v115, v81
	v_mov_b32_e32 v114, v131
	v_pk_add_f32 v[72:73], v[92:93], v[80:81]
	s_waitcnt lgkmcnt(0)
	v_mfma_f32_16x16x32_bf16 v[60:63], v[76:79], v[60:63], v[64:67]
	v_add_f32_e64 v72, v112, v72
	v_add_f32_e64 v73, v113, v73
	v_mov_b32_e32 v112, v173
	v_mfma_f32_16x16x32_bf16 v[32:35], v[76:79], v[68:71], v[32:35]
	v_add_f32_e64 v64, v90, v72
	v_add_f32_e64 v65, v91, v73
	v_pk_add_f32 v[64:65], v[96:97], v[64:65]
	s_nop 0
	v_pk_fma_f32 v[106:107], v[106:107], v[82:83], v[64:65]

; DEVI unsigned pk_bf16(float lo, float hi) { unsigned r; asm("v_cvt_pk_bf16_f32 %0, %1, %2" : "=v"(r) : "v"(lo), "v"(hi)); return r; }
; DEVI bf16x8 mk8(uint2 a, uint2 b) { union { uint4 u; bf16x8 v; } c; c.u = make_uint4(a.x, a.y, b.x, b.y); return c.v; }
; template <int DK, bool BIAS> ...
;     ...
;       for (int qi = 0; qi < 2; ++qi) {
;         float mx = -3e38f;
;         if (BIAS) {
; #pragma unroll
;           for (int kt = 0; kt < 4; ++kt) { const f32x4 nf = *(const f32x4*)(fkm + buf * 64 + 16 * kt + 4 * fq);
; #pragma unroll
;             for (int r = 0; r < 4; ++r) { const float t = fmaf(S[kt][qi][r], sc2, nf[r]); S[kt][qi][r] = t; mx = fmaxf(mx, t); } }
;         } else {
; #pragma unroll
;           for (int kt = 0; kt < 4; ++kt)
; #pragma unroll
;             for (int r = 0; r < 4; ++r) mx = fmaxf(mx, S[kt][qi][r]);
;           mx *= sc2;
;         }
;         mx = fmaxf(mx, __shfl_xor(mx, 16)); mx = fmaxf(mx, __shfl_xor(mx, 32));
;         const float mold = mrun[qi], mnew = fmaxf(mold, mx);
;         mrun[qi] = mnew;
;         float ps = 0.f;
; #pragma unroll
;         for (int kt = 0; kt < 4; ++kt)
; #pragma unroll
;           for (int r = 0; r < 4; ++r) { const float pv = BIAS ? __builtin_amdgcn_exp2f(S[kt][qi][r] - mnew) : __builtin_amdgcn_exp2f(fmaf(S[kt][qi][r], sc2, -mnew)); S[kt][qi][r] = pv; ps += pv; }
;         {
;           const float alpha = __builtin_amdgcn_exp2f(mold - mnew);
;           lrun[qi] *= alpha;
; #pragma unroll
;           for (int et = 0; et < 4; ++et) O[et][qi] *= alpha;
;         }
;         lrun[qi] += ps;
; #pragma unroll
;         for (int k2 = 0; k2 < 2; ++k2) { uint2 lo, hi; lo.x = pk_bf16(S[2 * k2][qi][0], S[2 * k2][qi][1]); lo.y = pk_bf16(S[2 * k2][qi][2], S[2 * k2][qi][3]);
;           hi.x = pk_bf16(S[2 * k2 + 1][qi][0], S[2 * k2 + 1][qi][1]); hi.y = pk_bf16(S[2 * k2 + 1][qi][2], S[2 * k2 + 1][qi][3]); pf[qi][k2] = mk8(lo, hi); }
;       }
.LBB0_1797:
	s_or_b64 exec, exec, s[18:19]
	ds_read_b128 v[174:177], v104 offset:37120
	ds_read_b128 v[194:197], v104 offset:37184
	ds_read_b128 v[242:245], v104 offset:37248
	ds_read_b128 v[246:249], v104 offset:37312
	s_mov_b32 s100, 0x3e38aa3b
	s_mov_b32 s101, 0x3e38aa3b
	v_cmp_lt_i32_e32 vcc, v186, v184
	s_nop 1
	v_cndmask_b32_e32 v250, v183, v186, vcc
	v_cmp_lt_i32_e32 vcc, v185, v184
	s_nop 1
	v_cndmask_b32_e32 v251, v183, v185, vcc
	v_lshlrev_b32_e32 v250, 2, v250
	v_lshlrev_b32_e32 v251, 2, v251
	s_waitcnt lgkmcnt(3)
	v_pk_fma_f32 v[210:211], v[80:81], s[100:101], v[174:175]
	v_pk_fma_f32 v[212:213], v[82:83], s[100:101], v[176:177]
	v_pk_fma_f32 v[226:227], v[64:65], s[100:101], v[174:175]
	v_pk_fma_f32 v[228:229], v[66:67], s[100:101], v[176:177]
	s_waitcnt lgkmcnt(2)
	v_pk_fma_f32 v[214:215], v[86:87], s[100:101], v[194:195]
	v_pk_fma_f32 v[216:217], v[88:89], s[100:101], v[196:197]
	v_pk_fma_f32 v[230:231], v[68:69], s[100:101], v[194:195]
	v_pk_fma_f32 v[232:233], v[70:71], s[100:101], v[196:197]
	s_waitcnt lgkmcnt(1)
	v_pk_fma_f32 v[218:219], v[90:91], s[100:101], v[242:243]
	v_pk_fma_f32 v[220:221], v[92:93], s[100:101], v[244:245]
	v_pk_fma_f32 v[234:235], v[72:73], s[100:101], v[242:243]
	v_pk_fma_f32 v[236:237], v[74:75], s[100:101], v[244:245]
	s_waitcnt lgkmcnt(0)
	v_pk_fma_f32 v[222:223], v[94:95], s[100:101], v[246:247]
	v_pk_fma_f32 v[224:225], v[96:97], s[100:101], v[248:249]
	v_pk_fma_f32 v[238:239], v[76:77], s[100:101], v[246:247]
	v_pk_fma_f32 v[240:241], v[78:79], s[100:101], v[248:249]
	v_max3_f32 v84, v210, s31, v211
	v_max3_f32 v85, v226, s31, v227
	v_max3_f32 v84, v84, v212, v213
	v_max3_f32 v85, v85, v228, v229
	v_max3_f32 v84, v84, v214, v215
	v_max3_f32 v85, v85, v230, v231
	v_max3_f32 v84, v84, v216, v217
	v_max3_f32 v85, v85, v232, v233
	v_max3_f32 v84, v84, v218, v219
	v_max3_f32 v85, v85, v234, v235
	v_max3_f32 v84, v84, v220, v221
	v_max3_f32 v85, v85, v236, v237
	v_max3_f32 v84, v84, v222, v223
	v_max3_f32 v85, v85, v238, v239
	v_max3_f32 v84, v84, v224, v225
	v_max3_f32 v85, v85, v240, v241
	ds_bpermute_b32 v86, v250, v84
	ds_bpermute_b32 v87, v250, v85
	s_waitcnt lgkmcnt(0)
	v_max_f32_e32 v84, v84, v86
	v_max_f32_e32 v85, v85, v87
	ds_bpermute_b32 v86, v251, v84
	ds_bpermute_b32 v87, v251, v85
	s_waitcnt lgkmcnt(0)
	v_max3_f32 v131, v114, v84, v86
	v_max3_f32 v173, v112, v85, v87
	v_sub_f32_e32 v84, v114, v131
	v_sub_f32_e32 v85, v112, v173
	v_exp_f32_e32 v126, v84
	v_exp_f32_e32 v82, v85
	v_sub_f32_e32 v86, 0, v131
	v_sub_f32_e32 v80, 0, v173
	v_pk_add_f32 v[210:211], v[210:211], v[86:87] op_sel_hi:[1,0]
	v_pk_add_f32 v[212:213], v[212:213], v[86:87] op_sel_hi:[1,0]
	v_pk_add_f32 v[226:227], v[226:227], v[80:81] op_sel_hi:[1,0]
	v_pk_add_f32 v[228:229], v[228:229], v[80:81] op_sel_hi:[1,0]
	v_pk_add_f32 v[214:215], v[214:215], v[86:87] op_sel_hi:[1,0]
	v_pk_add_f32 v[216:217], v[216:217], v[86:87] op_sel_hi:[1,0]
	v_pk_add_f32 v[230:231], v[230:231], v[80:81] op_sel_hi:[1,0]
	v_pk_add_f32 v[232:233], v[232:233], v[80:81] op_sel_hi:[1,0]
	v_pk_add_f32 v[218:219], v[218:219], v[86:87] op_sel_hi:[1,0]
	v_pk_add_f32 v[220:221], v[220:221], v[86:87] op_sel_hi:[1,0]
	v_pk_add_f32 v[234:235], v[234:235], v[80:81] op_sel_hi:[1,0]
	v_pk_add_f32 v[236:237], v[236:237], v[80:81] op_sel_hi:[1,0]
	v_pk_add_f32 v[222:223], v[222:223], v[86:87] op_sel_hi:[1,0]
	v_pk_add_f32 v[224:225], v[224:225], v[86:87] op_sel_hi:[1,0]
	v_pk_add_f32 v[238:239], v[238:239], v[80:81] op_sel_hi:[1,0]
	v_pk_add_f32 v[240:241], v[240:241], v[80:81] op_sel_hi:[1,0]
	v_exp_f32_e32 v155, v210
	v_exp_f32_e32 v154, v226
	v_exp_f32_e32 v157, v211
	v_exp_f32_e32 v156, v227
	v_exp_f32_e32 v151, v212
	v_exp_f32_e32 v150, v228
	v_exp_f32_e32 v153, v213
	v_exp_f32_e32 v152, v229
	v_exp_f32_e32 v117, v214
	v_exp_f32_e32 v116, v230
	v_exp_f32_e32 v119, v215
	v_exp_f32_e32 v118, v231
	v_exp_f32_e32 v123, v216
	v_exp_f32_e32 v122, v232
	v_exp_f32_e32 v121, v217
	v_exp_f32_e32 v120, v233
	v_exp_f32_e32 v125, v218
	v_exp_f32_e32 v124, v234
	v_exp_f32_e32 v89, v219
	v_exp_f32_e32 v88, v235
	v_exp_f32_e32 v95, v220
	v_exp_f32_e32 v94, v236
	v_exp_f32_e32 v115, v221
	v_exp_f32_e32 v114, v237
	v_exp_f32_e32 v93, v222
	v_exp_f32_e32 v92, v238
	v_exp_f32_e32 v113, v223
	v_exp_f32_e32 v112, v239
	v_exp_f32_e32 v91, v224
	v_exp_f32_e32 v90, v240
	v_exp_f32_e32 v97, v225
	v_exp_f32_e32 v96, v241
	v_pk_mul_f32 v[202:203], v[52:53], v[126:127] op_sel_hi:[1,0]
	v_pk_mul_f32 v[52:53], v[56:57], v[126:127] op_sel_hi:[1,0]
	v_pk_mul_f32 v[198:199], v[48:49], v[126:127] op_sel_hi:[1,0]
	v_pk_mul_f32 v[48:49], v[60:61], v[126:127] op_sel_hi:[1,0]
	v_add_u32_e32 v174, 0x6800, v170
	v_add_u32_e32 v175, 0x7000, v170
	v_pk_mul_f32 v[200:201], v[50:51], v[126:127] op_sel_hi:[1,0]
	v_add_u32_e32 v176, 0x7800, v170
	v_pk_mul_f32 v[204:205], v[54:55], v[126:127] op_sel_hi:[1,0]
	v_pk_add_f32 v[64:65], v[154:155], 0 op_sel_hi:[1,0]
	v_pk_add_f32 v[80:81], v[156:157], v[64:65]
	ds_read2_b64 v[64:67], v174 offset0:128 offset1:132
	ds_read2_b64 v[72:75], v175 offset0:160 offset1:164
	v_pk_mul_f32 v[46:47], v[46:47], v[82:83] op_sel_hi:[1,0]
	v_pk_mul_f32 v[44:45], v[44:45], v[82:83] op_sel_hi:[1,0]
	v_pk_mul_f32 v[54:55], v[58:59], v[126:127] op_sel_hi:[1,0]
	v_cvt_pk_bf16_f32 v56, v155, v157
	v_cvt_pk_bf16_f32 v57, v151, v153
	v_cvt_pk_bf16_f32 v58, v117, v119
	v_cvt_pk_bf16_f32 v59, v123, v121
	v_cvt_pk_bf16_f32 v68, v154, v156
	s_waitcnt lgkmcnt(1)
; DEVI unsigned pk_bf16(float lo, float hi) { unsigned r; asm("v_cvt_pk_bf16_f32 %0, %1, %2" : "=v"(r) : "v"(lo), "v"(hi)); return r; }
; DEVI bf16x8 mk8(uint2 a, uint2 b) { union { uint4 u; bf16x8 v; } c; c.u = make_uint4(a.x, a.y, b.x, b.y); return c.v; }
; #define MFMA(a, b, c) __builtin_amdgcn_mfma_f32_16x16x32_bf16((a), (b), (c), 0, 0, 0)
; template <int DK, bool BIAS> ...
;     ...
;         {
;           const float alpha = __builtin_amdgcn_exp2f(mold - mnew);
;           lrun[qi] *= alpha;
; #pragma unroll
;           for (int et = 0; et < 4; ++et) O[et][qi] *= alpha;
;         }
;         lrun[qi] += ps;
; #pragma unroll
;         for (int k2 = 0; k2 < 2; ++k2) { uint2 lo, hi; lo.x = pk_bf16(S[2 * k2][qi][0], S[2 * k2][qi][1]); lo.y = pk_bf16(S[2 * k2][qi][2], S[2 * k2][qi][3]);
;           hi.x = pk_bf16(S[2 * k2 + 1][qi][0], S[2 * k2 + 1][qi][1]); hi.y = pk_bf16(S[2 * k2 + 1][qi][2], S[2 * k2 + 1][qi][3]); pf[qi][k2] = mk8(lo, hi); }
;       }
; #pragma unroll
;       for (int k2 = 0; k2 < 2; ++k2)
; #pragma unroll
;         for (int et = 0; et < 4; ++et) {
;           const uint2 v0 = *(const uint2*)(Vtm + (buf * 64 + 16 * et + fr) * 72 + 32 * k2 + 4 * fq), v1 = *(const uint2*)(Vtm + (buf * 64 + 16 * et + fr) * 72 + 32 * k2 + 16 + 4 * fq);
;           const bf16x8 va = mk8(v0, v1);
; #pragma unroll
;           for (int qi = 0; qi < 2; ++qi) O[et][qi] = MFMA(va, pf[qi][k2], O[et][qi]);
;         }
	v_mfma_f32_16x16x32_bf16 v[76:79], v[64:67], v[56:59], v[198:201]
	v_cvt_pk_bf16_f32 v69, v150, v152
	v_cvt_pk_bf16_f32 v70, v116, v118
	v_cvt_pk_bf16_f32 v71, v122, v120
	v_mul_f32_e64 v42, v42, v82
	v_mul_f32_e64 v43, v43, v82
	v_mfma_f32_16x16x32_bf16 v[44:47], v[64:67], v[68:71], v[44:47]
	ds_read2_b64 v[64:67], v176 offset0:192 offset1:196
	v_pk_mul_f32 v[40:41], v[40:41], v[82:83] op_sel_hi:[1,0]
	v_add_u32_e32 v177, 0x8000, v170
	s_waitcnt lgkmcnt(1)
	v_mfma_f32_16x16x32_bf16 v[84:87], v[72:75], v[56:59], v[202:205]
	v_pk_mul_f32 v[50:51], v[62:63], v[126:127] op_sel_hi:[1,0]
	v_mfma_f32_16x16x32_bf16 v[40:43], v[72:75], v[68:71], v[40:43]
	ds_read2_b64 v[72:75], v177 offset0:224 offset1:228
	v_pk_mul_f32 v[38:39], v[38:39], v[82:83] op_sel_hi:[1,0]
	v_pk_mul_f32 v[36:37], v[36:37], v[82:83] op_sel_hi:[1,0]
	s_waitcnt lgkmcnt(1)
	v_mfma_f32_16x16x32_bf16 v[154:157], v[64:67], v[56:59], v[52:55]
	v_mul_f32_e64 v34, v34, v82
	v_mul_f32_e64 v35, v35, v82
	v_pk_mul_f32 v[32:33], v[32:33], v[82:83] op_sel_hi:[1,0]
	v_cvt_pk_bf16_f32 v60, v125, v89
	v_mfma_f32_16x16x32_bf16 v[36:39], v[64:67], v[68:71], v[36:39]
	ds_read2_b64 v[52:55], v174 offset0:136 offset1:140
	s_waitcnt lgkmcnt(1)
	v_mfma_f32_16x16x32_bf16 v[64:67], v[72:75], v[56:59], v[48:51]
	ds_read2_b64 v[56:59], v175 offset0:168 offset1:172
	v_cvt_pk_bf16_f32 v61, v95, v115
	v_cvt_pk_bf16_f32 v62, v93, v113
	v_cvt_pk_bf16_f32 v63, v91, v97
	s_nop 0
	v_mfma_f32_16x16x32_bf16 v[32:35], v[72:75], v[68:71], v[32:35]
	v_cvt_pk_bf16_f32 v68, v124, v88
	v_cvt_pk_bf16_f32 v69, v94, v114
	s_waitcnt lgkmcnt(1)
	v_mfma_f32_16x16x32_bf16 v[48:51], v[52:55], v[60:63], v[76:79]
	v_cvt_pk_bf16_f32 v70, v92, v112
	v_cvt_pk_bf16_f32 v71, v90, v96
	ds_read2_b64 v[72:75], v176 offset0:200 offset1:204
	s_nop 0
	v_mfma_f32_16x16x32_bf16 v[44:47], v[52:55], v[68:71], v[44:47]
	v_add_f32_e64 v52, v150, v80
	v_add_f32_e64 v53, v151, v81
	v_mov_b32_e32 v83, v126
	v_pk_add_f32 v[76:77], v[152:153], v[52:53]
	s_waitcnt lgkmcnt(1)
	v_mfma_f32_16x16x32_bf16 v[52:55], v[56:59], v[60:63], v[84:87]
	v_add_f32_e64 v76, v116, v76
	v_add_f32_e64 v77, v117, v77
	v_pk_add_f32 v[76:77], v[118:119], v[76:77]
	v_mfma_f32_16x16x32_bf16 v[40:43], v[56:59], v[68:71], v[40:43]
	v_add_f32_e64 v76, v122, v76
	v_add_f32_e64 v77, v123, v77
	v_pk_add_f32 v[56:57], v[120:121], v[76:77]
	ds_read2_b64 v[76:79], v177 offset0:232 offset1:236
	v_pk_add_f32 v[80:81], v[124:125], v[56:57]
	s_waitcnt lgkmcnt(1)
	v_mfma_f32_16x16x32_bf16 v[56:59], v[72:75], v[60:63], v[154:157]
	v_add_f32_e64 v80, v88, v80
	v_add_f32_e64 v81, v89, v81
	v_pk_add_f32 v[80:81], v[94:95], v[80:81]
	v_mfma_f32_16x16x32_bf16 v[36:39], v[72:75], v[68:71], v[36:39]
	v_add_f32_e64 v80, v114, v80
	v_add_f32_e64 v81, v115, v81
	v_mov_b32_e32 v114, v131
	v_pk_add_f32 v[72:73], v[92:93], v[80:81]
	s_waitcnt lgkmcnt(0)
	v_mfma_f32_16x16x32_bf16 v[60:63], v[76:79], v[60:63], v[64:67]
	v_add_f32_e64 v72, v112, v72
	v_add_f32_e64 v73, v113, v73
	v_mov_b32_e32 v112, v173
	v_mfma_f32_16x16x32_bf16 v[32:35], v[76:79], v[68:71], v[32:35]
	v_add_f32_e64 v64, v90, v72
	v_add_f32_e64 v65, v91, v73
	v_pk_add_f32 v[64:65], v[96:97], v[64:65]
	s_nop 0
	v_pk_fma_f32 v[106:107], v[106:107], v[82:83], v[64:65]
